# input LayerNorm (launch prologue): gamma/beta hoisted out of the row loop like P5; s_nop guard before the register copies
# speedup vs baseline: 1.0330x; 1.0017x over previous
; __device__ __forceinline__ unsigned cvt_pk_bf16(float lo, float hi) { unsigned r; asm volatile("v_cvt_pk_bf16_f32 %0, %1, %2" : "=v"(r) : "v"(lo), "v"(hi)); return r; }
; __device__ __forceinline__ void ln_row2(const float* x0, const float* x1, const float* g, const float* b, float* o0, float* o1, bf16_t* ob0, bf16_t* ob1, int lane, float* st0, float* st1, bool wx) {
;     ...
; #pragma unroll
;     for (int j = 0; j < 4; ++j) { const f32x4 gg = ((const f32x4*)g)[lane + 64 * j], bb = ((const f32x4*)b)[lane + 64 * j];
;         const f32x4 y0 = v[j] * rstd0 * gg + bb, y1 = w[j] * rstd1 * gg + bb;
;         if (wx) { ((f32x4*)o0)[lane + 64 * j] = y0; ((f32x4*)o1)[lane + 64 * j] = y1; }
;         u32x2 p0; p0.x = cvt_pk_bf16(y0.x, y0.y); p0.y = cvt_pk_bf16(y0.z, y0.w); ((u32x2*)ob0)[lane + 64 * j] = p0;
;         u32x2 p1; p1.x = cvt_pk_bf16(y1.x, y1.y); p1.y = cvt_pk_bf16(y1.z, y1.w); ((u32x2*)ob1)[lane + 64 * j] = p1; }
; __global__ void __launch_bounds__(NWAVES * 64, 2) mega_fwd(Args args) {
;     ...
;         for (int m = gw; m < NTOK; m += 2 * NGW) {
;             const int m1 = m + NGW;
;             const float* src = (m < NP) ? args.in[0] + (size_t)m * DM : args.in[1] + (size_t)(m - NP) * DM;
;             if (m1 < NTOK) { const float* src1 = (m1 < NP) ? args.in[0] + (size_t)m1 * DM : args.in[1] + (size_t)(m1 - NP) * DM;
;                 ln_row2(src, src1, args.in[4], args.in[5], X + (size_t)m * DM, X + (size_t)m1 * DM, xb + (size_t)m * DM, xb + (size_t)m1 * DM, lane, rstat + 2 * (size_t)m, rstat + 2 * (size_t)m1, false); }
;             else ln_row(src, args.in[4], args.in[5], X + (size_t)m * DM, xb + (size_t)m * DM, lane, rstat + 2 * (size_t)m, false);
.LBB0_68:
	s_add_i32 s26, s26, s18
	v_readlane_b32 s0, v251, 11
	v_readlane_b32 s1, v251, 12
	s_add_u32 s4, s0, 0x9b00000
	s_addc_u32 s5, s1, 0
	s_add_u32 s58, s0, 0x15b00000
	v_writelane_b32 v251, s4, 53
	s_addc_u32 s59, s1, 0
	s_mul_i32 s1, s66, 0x4800
	v_writelane_b32 v251, s5, 54
	s_mul_hi_i32 s0, s66, 0x4800
	s_add_u32 s1, s58, s1
	v_writelane_b32 v251, s1, 55
	s_addc_u32 s0, s59, s0
	v_writelane_b32 v251, s0, 56
	v_mbcnt_lo_u32_b32 v146, -1, 0
	v_readlane_b32 s0, v251, 51
	v_readlane_b32 s1, v251, 52
	s_cmp_gt_i32 s0, 0x17fff
	v_cmp_eq_u32_e64 s[0:1], 0, v34
	v_readlane_b32 s4, v251, 49
	v_readlane_b32 s5, v251, 50
	s_cbranch_scc1 .LBB0_83
	v_readlane_b32 s68, v251, 13
	v_readlane_b32 s76, v251, 21
	v_readlane_b32 s77, v251, 22
	v_mov_b32_e32 v37, 0
	v_readlane_b32 s78, v251, 23
	v_readlane_b32 s79, v251, 24
	s_mov_b64 s[60:61], s[76:77]
	v_readlane_b32 s6, v251, 53
	v_lshlrev_b32_e32 v36, 4, v34
	s_mov_b64 s[62:63], s[78:79]
	v_mov_b32_e32 v3, v37
	v_readlane_b32 s7, v251, 54
	v_mbcnt_hi_u32_b32 v48, -1, v146
	v_lshl_add_u64 v[38:39], s[60:61], 0, v[36:37]
	v_lshl_add_u64 v[40:41], s[62:63], 0, v[36:37]
	v_lshl_add_u64 v[42:43], s[6:7], 0, v[2:3]
	v_or_b32_e32 v36, 0x600, v2
	v_and_b32_e32 v2, 64, v48
	s_mov_b32 s13, 0
	v_lshl_add_u64 v[44:45], s[6:7], 0, v[36:37]
	v_mov_b32_e32 v1, 0x3727c5ac
	s_mov_b32 s20, 0xf800000
	v_mov_b32_e32 v35, 0x260
	v_lshlrev_b32_e32 v47, 4, v34
	v_add_u32_e32 v49, 64, v2
	v_xor_b32_e32 v50, 1, v48
	v_xor_b32_e32 v51, 2, v48
	v_xor_b32_e32 v52, 4, v48
	v_xor_b32_e32 v53, 8, v48
	v_xor_b32_e32 v54, 16, v48
	v_xor_b32_e32 v55, 32, v48
	v_readlane_b32 s16, v251, 51
	v_readlane_b32 s69, v251, 14
	v_readlane_b32 s70, v251, 15
	v_readlane_b32 s71, v251, 16
	v_readlane_b32 s72, v251, 17
	v_readlane_b32 s73, v251, 18
	v_readlane_b32 s74, v251, 19
	v_readlane_b32 s75, v251, 20
	v_readlane_b32 s80, v251, 25
	v_readlane_b32 s81, v251, 26
	v_readlane_b32 s82, v251, 27
	v_readlane_b32 s83, v251, 28
	v_readlane_b32 s17, v251, 52
	global_load_dwordx4 v[84:87], v[38:39], off
	global_load_dwordx4 v[104:107], v[40:41], off
	global_load_dwordx4 v[88:91], v[38:39], off offset:1024
	global_load_dwordx4 v[108:111], v[40:41], off offset:1024
	global_load_dwordx4 v[92:95], v[38:39], off offset:2048
	global_load_dwordx4 v[112:115], v[40:41], off offset:2048
	global_load_dwordx4 v[100:103], v[38:39], off offset:3072
	global_load_dwordx4 v[132:135], v[40:41], off offset:3072
	s_branch .LBB0_72
.LBB0_70:
	s_or_b64 exec, exec, s[4:5]
	s_lshl_b64 s[6:7], s[16:17], 11
	s_lshl_b64 s[4:5], s[14:15], 11
	v_pk_mul_f32 v[30:31], v[30:31], v[36:37] op_sel_hi:[1,0]
	v_pk_mul_f32 v[26:27], v[26:27], v[46:47] op_sel_hi:[1,0]
	v_pk_mul_f32 v[32:33], v[32:33], v[36:37] op_sel_hi:[1,0]
	v_pk_mul_f32 v[28:29], v[28:29], v[46:47] op_sel_hi:[1,0]
	v_lshl_add_u64 v[64:65], v[42:43], 0, s[6:7]
	v_lshl_add_u64 v[66:67], v[42:43], 0, s[4:5]
	v_pk_mul_f32 v[22:23], v[22:23], v[36:37] op_sel_hi:[1,0]
	v_pk_mul_f32 v[18:19], v[18:19], v[46:47] op_sel_hi:[1,0]
	v_pk_mul_f32 v[24:25], v[24:25], v[36:37] op_sel_hi:[1,0]
	v_pk_mul_f32 v[20:21], v[20:21], v[46:47] op_sel_hi:[1,0]
	v_pk_mul_f32 v[14:15], v[14:15], v[36:37] op_sel_hi:[1,0]
	v_pk_mul_f32 v[10:11], v[10:11], v[46:47] op_sel_hi:[1,0]
	v_pk_mul_f32 v[16:17], v[16:17], v[36:37] op_sel_hi:[1,0]
	v_pk_mul_f32 v[12:13], v[12:13], v[46:47] op_sel_hi:[1,0]
	v_pk_mul_f32 v[6:7], v[6:7], v[36:37] op_sel_hi:[1,0]
	v_pk_mul_f32 v[2:3], v[2:3], v[46:47] op_sel_hi:[1,0]
	v_pk_mul_f32 v[8:9], v[8:9], v[36:37] op_sel_hi:[1,0]
	v_pk_mul_f32 v[4:5], v[4:5], v[46:47] op_sel_hi:[1,0]
	s_nop 1
	v_mov_b32_e32 v56, v84
	v_mov_b32_e32 v57, v85
	v_mov_b32_e32 v58, v86
	v_mov_b32_e32 v59, v87
	v_mov_b32_e32 v60, v104
	v_mov_b32_e32 v61, v105
	v_mov_b32_e32 v62, v106
	v_mov_b32_e32 v63, v107
	v_pk_fma_f32 v[30:31], v[30:31], v[56:57], v[60:61]
	v_pk_fma_f32 v[26:27], v[26:27], v[56:57], v[60:61]
	v_pk_fma_f32 v[32:33], v[32:33], v[58:59], v[62:63]
	v_pk_fma_f32 v[28:29], v[28:29], v[58:59], v[62:63]
	v_cvt_pk_bf16_f32 v30, v30, v31
	v_cvt_pk_bf16_f32 v31, v32, v33
	global_store_dwordx2 v[64:65], v[30:31], off
	v_cvt_pk_bf16_f32 v26, v26, v27
	v_cvt_pk_bf16_f32 v27, v28, v29
	global_store_dwordx2 v[66:67], v[26:27], off
	s_nop 0
	s_nop 1
	v_mov_b32_e32 v26, v88
	v_mov_b32_e32 v27, v89
	v_mov_b32_e32 v28, v90
	v_mov_b32_e32 v29, v91
	v_mov_b32_e32 v30, v108
	v_mov_b32_e32 v31, v109
	v_mov_b32_e32 v32, v110
	v_mov_b32_e32 v33, v111
	v_pk_fma_f32 v[22:23], v[22:23], v[26:27], v[30:31]
	v_pk_fma_f32 v[18:19], v[18:19], v[26:27], v[30:31]
	v_pk_fma_f32 v[24:25], v[24:25], v[28:29], v[32:33]
	v_pk_fma_f32 v[20:21], v[20:21], v[28:29], v[32:33]
	v_cvt_pk_bf16_f32 v22, v22, v23
	v_cvt_pk_bf16_f32 v23, v24, v25
	global_store_dwordx2 v[64:65], v[22:23], off offset:512
	v_cvt_pk_bf16_f32 v18, v18, v19
	v_cvt_pk_bf16_f32 v19, v20, v21
	global_store_dwordx2 v[66:67], v[18:19], off offset:512
	s_nop 0
	s_nop 1
	v_mov_b32_e32 v18, v92
	v_mov_b32_e32 v19, v93
	v_mov_b32_e32 v20, v94
	v_mov_b32_e32 v21, v95
	v_mov_b32_e32 v22, v112
	v_mov_b32_e32 v23, v113
	v_mov_b32_e32 v24, v114
	v_mov_b32_e32 v25, v115
	v_pk_fma_f32 v[14:15], v[14:15], v[18:19], v[22:23]
	v_pk_fma_f32 v[10:11], v[10:11], v[18:19], v[22:23]
	v_pk_fma_f32 v[16:17], v[16:17], v[20:21], v[24:25]
	v_pk_fma_f32 v[12:13], v[12:13], v[20:21], v[24:25]
	v_cvt_pk_bf16_f32 v14, v14, v15
	v_cvt_pk_bf16_f32 v15, v16, v17
	global_store_dwordx2 v[64:65], v[14:15], off offset:1024
	v_cvt_pk_bf16_f32 v10, v10, v11
	v_cvt_pk_bf16_f32 v11, v12, v13
	global_store_dwordx2 v[66:67], v[10:11], off offset:1024
	s_nop 0
	s_nop 1
	v_mov_b32_e32 v10, v100
	v_mov_b32_e32 v11, v101
	v_mov_b32_e32 v12, v102
	v_mov_b32_e32 v13, v103
	v_mov_b32_e32 v14, v132
	v_mov_b32_e32 v15, v133
	v_mov_b32_e32 v16, v134
	v_mov_b32_e32 v17, v135
	v_pk_fma_f32 v[6:7], v[6:7], v[10:11], v[14:15]
	v_pk_fma_f32 v[2:3], v[2:3], v[10:11], v[14:15]
	v_pk_fma_f32 v[8:9], v[8:9], v[12:13], v[16:17]
	v_pk_fma_f32 v[4:5], v[4:5], v[12:13], v[16:17]
	v_cvt_pk_bf16_f32 v6, v6, v7
	v_cvt_pk_bf16_f32 v7, v8, v9
	global_store_dwordx2 v[64:65], v[6:7], off offset:1536
	v_cvt_pk_bf16_f32 v2, v2, v3
	v_cvt_pk_bf16_f32 v3, v4, v5

; __device__ __forceinline__ unsigned cvt_pk_bf16(float lo, float hi) { unsigned r; asm volatile("v_cvt_pk_bf16_f32 %0, %1, %2" : "=v"(r) : "v"(lo), "v"(hi)); return r; }
; __device__ __forceinline__ void ln_row(const float* xrow, const float* g, const float* b, float* orow, bf16_t* obrow, int lane, float* st, bool wx) {
;     ...
; #pragma unroll
;     for (int j = 0; j < 4; ++j) { const f32x4 gg = ((const f32x4*)g)[lane + 64 * j], bb = ((const f32x4*)b)[lane + 64 * j];
;         const f32x4 y = v[j] * rstd * gg + bb;
;         if (wx) ((f32x4*)orow)[lane + 64 * j] = y;
;         u32x2 w; w.x = cvt_pk_bf16(y.x, y.y); w.y = cvt_pk_bf16(y.z, y.w);
;         ((u32x2*)obrow)[lane + 64 * j] = w; }
.LBB0_75:
	s_or_b64 exec, exec, s[4:5]
	s_lshl_b64 s[4:5], s[16:17], 11
	v_pk_mul_f32 v[14:15], v[14:15], v[18:19] op_sel_hi:[1,0]
	v_pk_mul_f32 v[16:17], v[16:17], v[18:19] op_sel_hi:[1,0]
	v_lshl_add_u64 v[28:29], v[42:43], 0, s[4:5]
	v_pk_mul_f32 v[10:11], v[10:11], v[18:19] op_sel_hi:[1,0]
	v_pk_mul_f32 v[12:13], v[12:13], v[18:19] op_sel_hi:[1,0]
	v_pk_mul_f32 v[6:7], v[6:7], v[18:19] op_sel_hi:[1,0]
	v_pk_mul_f32 v[8:9], v[8:9], v[18:19] op_sel_hi:[1,0]
	v_pk_mul_f32 v[2:3], v[2:3], v[18:19] op_sel_hi:[1,0]
	v_pk_mul_f32 v[4:5], v[4:5], v[18:19] op_sel_hi:[1,0]
	s_mov_b64 s[18:19], 0
	s_nop 1
	v_mov_b32_e32 v20, v84
	v_mov_b32_e32 v21, v85
	v_mov_b32_e32 v22, v86
	v_mov_b32_e32 v23, v87
	v_mov_b32_e32 v24, v104
	v_mov_b32_e32 v25, v105
	v_mov_b32_e32 v26, v106
	v_mov_b32_e32 v27, v107
	v_pk_fma_f32 v[14:15], v[14:15], v[20:21], v[24:25]
	v_pk_fma_f32 v[16:17], v[16:17], v[22:23], v[26:27]
	v_cvt_pk_bf16_f32 v14, v14, v15
	s_nop 0
	v_cvt_pk_bf16_f32 v15, v16, v17
	global_store_dwordx2 v[28:29], v[14:15], off
	s_nop 0
	s_nop 1
	v_mov_b32_e32 v14, v88
	v_mov_b32_e32 v15, v89
	v_mov_b32_e32 v16, v90
	v_mov_b32_e32 v17, v91
	v_mov_b32_e32 v20, v108
	v_mov_b32_e32 v21, v109
	v_mov_b32_e32 v22, v110
	v_mov_b32_e32 v23, v111
	v_pk_fma_f32 v[10:11], v[10:11], v[14:15], v[20:21]
	v_pk_fma_f32 v[12:13], v[12:13], v[16:17], v[22:23]
	v_cvt_pk_bf16_f32 v10, v10, v11
	s_nop 0
	v_cvt_pk_bf16_f32 v11, v12, v13
	global_store_dwordx2 v[28:29], v[10:11], off offset:512
	s_nop 0
	s_nop 1
	v_mov_b32_e32 v10, v92
	v_mov_b32_e32 v11, v93
	v_mov_b32_e32 v12, v94
	v_mov_b32_e32 v13, v95
	v_mov_b32_e32 v14, v112
	v_mov_b32_e32 v15, v113
	v_mov_b32_e32 v16, v114
	v_mov_b32_e32 v17, v115
	v_pk_fma_f32 v[6:7], v[6:7], v[10:11], v[14:15]
	v_pk_fma_f32 v[8:9], v[8:9], v[12:13], v[16:17]
	v_cvt_pk_bf16_f32 v6, v6, v7
	s_nop 0
	v_cvt_pk_bf16_f32 v7, v8, v9
	global_store_dwordx2 v[28:29], v[6:7], off offset:1024
	s_nop 0
	s_nop 1
	v_mov_b32_e32 v6, v100
	v_mov_b32_e32 v7, v101
	v_mov_b32_e32 v8, v102
	v_mov_b32_e32 v9, v103
	v_mov_b32_e32 v10, v132
	v_mov_b32_e32 v11, v133
	v_mov_b32_e32 v12, v134
	v_mov_b32_e32 v13, v135
	v_pk_fma_f32 v[2:3], v[2:3], v[6:7], v[10:11]
	v_pk_fma_f32 v[4:5], v[4:5], v[8:9], v[12:13]
	v_cvt_pk_bf16_f32 v2, v2, v3
	s_nop 0
	v_cvt_pk_bf16_f32 v3, v4, v5

; __device__ __forceinline__ unsigned cvt_pk_bf16(float lo, float hi) { unsigned r; asm volatile("v_cvt_pk_bf16_f32 %0, %1, %2" : "=v"(r) : "v"(lo), "v"(hi)); return r; }
; __device__ __forceinline__ void ln_row(const float* xrow, const float* g, const float* b, float* orow, bf16_t* obrow, int lane, float* st, bool wx) {
;     ...
; #pragma unroll
;     for (int j = 0; j < 4; ++j) { const f32x4 gg = ((const f32x4*)g)[lane + 64 * j], bb = ((const f32x4*)b)[lane + 64 * j];
;         const f32x4 y = v[j] * rstd * gg + bb;
;         if (wx) ((f32x4*)orow)[lane + 64 * j] = y;
;         u32x2 w; w.x = cvt_pk_bf16(y.x, y.y); w.y = cvt_pk_bf16(y.z, y.w);
;         ((u32x2*)obrow)[lane + 64 * j] = w; }
.LBB0_869:
	s_or_b64 exec, exec, s[0:1]
	v_pk_mul_f32 v[2:3], v[18:19], v[20:21] op_sel_hi:[1,0]
	v_pk_mul_f32 v[10:11], v[12:13], v[20:21] op_sel_hi:[1,0]
	v_cndmask_b32_e64 v12, 0, 1, s[26:27]
	v_lshl_add_u64 v[22:23], s[42:43], 0, v[96:97]
	v_cmp_ne_u32_e64 s[38:39], 1, v12
	s_andn2_b64 vcc, exec, s[26:27]
	s_nop 1
	v_mov_b32_e32 v24, v80
	v_mov_b32_e32 v25, v81
	v_mov_b32_e32 v26, v82
	v_mov_b32_e32 v27, v83
	v_mov_b32_e32 v28, v98
	v_mov_b32_e32 v29, v99
	v_mov_b32_e32 v30, v100
	v_mov_b32_e32 v31, v101
	v_pk_fma_f32 v[12:13], v[2:3], v[26:27], v[30:31]
	v_pk_fma_f32 v[10:11], v[10:11], v[24:25], v[28:29]
	s_cbranch_vccnz .LBB0_871
	global_store_dwordx4 v[22:23], v[10:13], off
.LBB0_871:
	v_cvt_pk_bf16_f32 v2, v10, v11
	s_nop 1
	v_lshl_add_u64 v[10:11], s[34:35], 1, v[38:39]
	v_cvt_pk_bf16_f32 v3, v12, v13
	global_store_dwordx2 v[10:11], v[2:3], off
	v_mov_b32_e32 v21, v20
	v_mov_b32_e32 v12, v20
	v_mov_b32_e32 v13, v20
	v_pk_mul_f32 v[2:3], v[14:15], v[12:13]
	v_pk_mul_f32 v[14:15], v[4:5], v[20:21]
	s_and_b64 vcc, exec, s[38:39]
	s_nop 1
	v_mov_b32_e32 v24, v84
	v_mov_b32_e32 v25, v85
	v_mov_b32_e32 v26, v86
	v_mov_b32_e32 v27, v87
	v_mov_b32_e32 v28, v102
	v_mov_b32_e32 v29, v103
	v_mov_b32_e32 v30, v104
	v_mov_b32_e32 v31, v105
	v_pk_fma_f32 v[4:5], v[2:3], v[26:27], v[30:31]
	v_pk_fma_f32 v[2:3], v[14:15], v[24:25], v[28:29]
	s_cbranch_vccnz .LBB0_873
	global_store_dwordx4 v[22:23], v[2:5], off offset:1024
.LBB0_873:
	s_nop 1
	v_cvt_pk_bf16_f32 v2, v2, v3
	v_cvt_pk_bf16_f32 v3, v4, v5
	global_store_dwordx2 v[10:11], v[2:3], off offset:512
	s_nop 0
	v_pk_mul_f32 v[12:13], v[16:17], v[12:13]
	v_pk_mul_f32 v[8:9], v[8:9], v[20:21]
	s_and_b64 vcc, exec, s[38:39]
	s_nop 1
	v_mov_b32_e32 v2, v88
	v_mov_b32_e32 v3, v89
	v_mov_b32_e32 v4, v90
	v_mov_b32_e32 v5, v91
	v_mov_b32_e32 v24, v106
	v_mov_b32_e32 v25, v107
	v_mov_b32_e32 v26, v108
	v_mov_b32_e32 v27, v109
	v_pk_fma_f32 v[4:5], v[12:13], v[4:5], v[26:27]
	v_pk_fma_f32 v[2:3], v[8:9], v[2:3], v[24:25]
	s_cbranch_vccnz .LBB0_875
	global_store_dwordx4 v[22:23], v[2:5], off offset:2048
.LBB0_875:
	s_nop 1
	v_cvt_pk_bf16_f32 v2, v2, v3
	v_cvt_pk_bf16_f32 v3, v4, v5
	global_store_dwordx2 v[10:11], v[2:3], off offset:1024
	s_nop 0
	v_mov_b32_e32 v2, v20
	v_mov_b32_e32 v3, v20
	v_pk_mul_f32 v[0:1], v[0:1], v[20:21]
	v_pk_mul_f32 v[2:3], v[6:7], v[2:3]
	s_and_b64 vcc, exec, s[38:39]
	s_nop 1
	v_mov_b32_e32 v8, v92
	v_mov_b32_e32 v9, v93
	v_mov_b32_e32 v10, v94
	v_mov_b32_e32 v11, v95
	v_mov_b32_e32 v12, v110
	v_mov_b32_e32 v13, v111
	v_mov_b32_e32 v14, v112
	v_mov_b32_e32 v15, v113
	v_pk_fma_f32 v[2:3], v[2:3], v[10:11], v[14:15]
	v_pk_fma_f32 v[0:1], v[0:1], v[8:9], v[12:13]
	s_cbranch_vccnz .LBB0_877
	global_store_dwordx4 v[22:23], v[0:3], off offset:3072

; __device__ __forceinline__ unsigned cvt_pk_bf16(float lo, float hi) { unsigned r; asm volatile("v_cvt_pk_bf16_f32 %0, %1, %2" : "=v"(r) : "v"(lo), "v"(hi)); return r; }
; __device__ __forceinline__ void ln_row2(const float* x0, const float* x1, const float* g, const float* b, float* o0, float* o1, bf16_t* ob0, bf16_t* ob1, int lane, float* st0, float* st1, bool wx) {
;     ...
; #pragma unroll
;     for (int j = 0; j < 4; ++j) { const f32x4 gg = ((const f32x4*)g)[lane + 64 * j], bb = ((const f32x4*)b)[lane + 64 * j];
;         const f32x4 y0 = v[j] * rstd0 * gg + bb, y1 = w[j] * rstd1 * gg + bb;
;         if (wx) { ((f32x4*)o0)[lane + 64 * j] = y0; ((f32x4*)o1)[lane + 64 * j] = y1; }
;         u32x2 p0; p0.x = cvt_pk_bf16(y0.x, y0.y); p0.y = cvt_pk_bf16(y0.z, y0.w); ((u32x2*)ob0)[lane + 64 * j] = p0;
;         u32x2 p1; p1.x = cvt_pk_bf16(y1.x, y1.y); p1.y = cvt_pk_bf16(y1.z, y1.w); ((u32x2*)ob1)[lane + 64 * j] = p1; }
.LBB0_881:
	s_or_b64 exec, exec, s[0:1]
	v_pk_mul_f32 v[6:7], v[50:51], v[54:55] op_sel_hi:[1,0]
	v_pk_mul_f32 v[14:15], v[28:29], v[54:55] op_sel_hi:[1,0]
	v_pk_mul_f32 v[18:19], v[26:27], v[56:57] op_sel_hi:[1,0]
	v_pk_mul_f32 v[22:23], v[24:25], v[56:57] op_sel_hi:[1,0]
	v_cndmask_b32_e64 v24, 0, 1, s[26:27]
	v_lshl_add_u64 v[58:59], s[42:43], 0, v[96:97]
	v_cmp_ne_u32_e64 s[38:39], 1, v24
	s_andn2_b64 vcc, exec, s[26:27]
	s_nop 1
	v_mov_b32_e32 v60, v80
	v_mov_b32_e32 v61, v81
	v_mov_b32_e32 v62, v82
	v_mov_b32_e32 v63, v83
	v_mov_b32_e32 v64, v98
	v_mov_b32_e32 v65, v99
	v_mov_b32_e32 v66, v100
	v_mov_b32_e32 v67, v101
	v_pk_fma_f32 v[28:29], v[6:7], v[62:63], v[66:67]
	v_pk_fma_f32 v[26:27], v[14:15], v[60:61], v[64:65]
	v_pk_fma_f32 v[24:25], v[18:19], v[62:63], v[66:67]
	v_pk_fma_f32 v[22:23], v[22:23], v[60:61], v[64:65]
	s_cbranch_vccnz .LBB0_883
	global_store_dwordx4 v[58:59], v[26:29], off
	global_store_dwordx4 v[44:45], v[22:25], off
.LBB0_883:
	s_lshl_b64 s[0:1], s[24:25], 10
	v_cvt_pk_bf16_f32 v6, v26, v27
	v_lshl_add_u64 v[26:27], s[34:35], 1, v[38:39]
	v_cvt_pk_bf16_f32 v7, v28, v29
	global_store_dwordx2 v[26:27], v[6:7], off
	v_cvt_pk_bf16_f32 v6, v22, v23
	v_lshl_add_u64 v[22:23], s[0:1], 1, v[38:39]
	v_cvt_pk_bf16_f32 v7, v24, v25
	global_store_dwordx2 v[22:23], v[6:7], off
	v_mov_b32_e32 v6, v54
	v_mov_b32_e32 v7, v54
	v_mov_b32_e32 v55, v54
	v_mov_b32_e32 v57, v56
	v_pk_mul_f32 v[14:15], v[48:49], v[6:7]
	v_mov_b32_e32 v24, v56
	v_mov_b32_e32 v25, v56
	v_pk_mul_f32 v[18:19], v[20:21], v[54:55]
	v_pk_mul_f32 v[28:29], v[16:17], v[56:57]
	s_and_b64 vcc, exec, s[38:39]
	s_nop 1
	v_mov_b32_e32 v60, v84
	v_mov_b32_e32 v61, v85
	v_mov_b32_e32 v62, v86
	v_mov_b32_e32 v63, v87
	v_mov_b32_e32 v64, v102
	v_mov_b32_e32 v65, v103
	v_mov_b32_e32 v66, v104
	v_mov_b32_e32 v67, v105
	v_pk_fma_f32 v[20:21], v[14:15], v[62:63], v[66:67]
	v_pk_mul_f32 v[14:15], v[52:53], v[24:25]
	v_pk_fma_f32 v[18:19], v[18:19], v[60:61], v[64:65]
	v_pk_fma_f32 v[16:17], v[14:15], v[62:63], v[66:67]
	v_pk_fma_f32 v[14:15], v[28:29], v[60:61], v[64:65]
	s_cbranch_vccnz .LBB0_885
	global_store_dwordx4 v[58:59], v[18:21], off offset:1024
	global_store_dwordx4 v[44:45], v[14:17], off offset:1024
.LBB0_885:
	s_nop 0
	v_cvt_pk_bf16_f32 v18, v18, v19
	v_cvt_pk_bf16_f32 v19, v20, v21
	global_store_dwordx2 v[26:27], v[18:19], off offset:512
	v_cvt_pk_bf16_f32 v14, v14, v15
	v_cvt_pk_bf16_f32 v15, v16, v17
	global_store_dwordx2 v[22:23], v[14:15], off offset:512
	s_nop 0
	v_pk_mul_f32 v[6:7], v[46:47], v[6:7]
	v_pk_mul_f32 v[28:29], v[12:13], v[54:55]
	v_pk_mul_f32 v[24:25], v[10:11], v[24:25]
	v_pk_mul_f32 v[46:47], v[8:9], v[56:57]
	s_and_b64 vcc, exec, s[38:39]
	s_nop 1
	v_mov_b32_e32 v14, v88
	v_mov_b32_e32 v15, v89
	v_mov_b32_e32 v16, v90
	v_mov_b32_e32 v17, v91
	v_mov_b32_e32 v18, v106
	v_mov_b32_e32 v19, v107
	v_mov_b32_e32 v20, v108
	v_mov_b32_e32 v21, v109
	v_pk_fma_f32 v[12:13], v[6:7], v[16:17], v[20:21]
	v_pk_fma_f32 v[10:11], v[28:29], v[14:15], v[18:19]
	v_pk_fma_f32 v[8:9], v[24:25], v[16:17], v[20:21]
	v_pk_fma_f32 v[6:7], v[46:47], v[14:15], v[18:19]
	s_cbranch_vccnz .LBB0_887
	global_store_dwordx4 v[58:59], v[10:13], off offset:2048
	global_store_dwordx4 v[44:45], v[6:9], off offset:2048
.LBB0_887:
	s_nop 0
	v_cvt_pk_bf16_f32 v10, v10, v11
	v_cvt_pk_bf16_f32 v11, v12, v13
	global_store_dwordx2 v[26:27], v[10:11], off offset:1024
	v_cvt_pk_bf16_f32 v6, v6, v7
	v_cvt_pk_bf16_f32 v7, v8, v9
	global_store_dwordx2 v[22:23], v[6:7], off offset:1024
	v_mov_b32_e32 v6, v54
	v_mov_b32_e32 v7, v54
	v_mov_b32_e32 v16, v56
	v_mov_b32_e32 v17, v56
	v_pk_mul_f32 v[0:1], v[0:1], v[54:55]
	v_pk_mul_f32 v[18:19], v[4:5], v[56:57]
	v_pk_mul_f32 v[2:3], v[2:3], v[6:7]
	v_pk_mul_f32 v[16:17], v[30:31], v[16:17]
	s_and_b64 vcc, exec, s[38:39]
	s_nop 1
	v_mov_b32_e32 v8, v92
	v_mov_b32_e32 v9, v93
	v_mov_b32_e32 v10, v94
	v_mov_b32_e32 v11, v95
	v_mov_b32_e32 v12, v110
	v_mov_b32_e32 v13, v111
	v_mov_b32_e32 v14, v112
	v_mov_b32_e32 v15, v113
	v_pk_fma_f32 v[6:7], v[2:3], v[10:11], v[14:15]
	v_pk_fma_f32 v[4:5], v[0:1], v[8:9], v[12:13]
	v_pk_fma_f32 v[2:3], v[16:17], v[10:11], v[14:15]
	v_pk_fma_f32 v[0:1], v[18:19], v[8:9], v[12:13]
	s_cbranch_vccnz .LBB0_889
	global_store_dwordx4 v[58:59], v[4:7], off offset:3072
	global_store_dwordx4 v[44:45], v[0:3], off offset:3072
